# G1 gate tiles: sigmoids computed per 16-value group right before that group's stores (store path overlaps the remaining sigmoid VALU)
# speedup vs baseline: 1.0068x; 1.0068x over previous
; DI size_t pidx(size_t row, int col) { return (size_t)(col >> 8) * ((size_t)TH * 256) + row * 256 + (size_t)(col & 255); }
; DI unsigned pk2(float lo, float hi) { return pg8::cvt_pk_bf16(lo, hi); }
; DI float sigmoidf_(float v) { return __builtin_amdgcn_rcpf(1.0f + __expf(-v)); }
;     DI void operator()(const f32x4 (&acc)[2][2][4][2], const Unit& u, int wr, int wc, int fr, int fq) const {
;     ...
;             const int col0 = u.pn * 256 + wc * 32 + 8 * fq; const bool sg = u.pn >= 26;
; #pragma unroll
;             for (int ai = 0; ai < 2; ++ai)
; #pragma unroll
;                 for (int m = 0; m < 4; ++m) { bf16* rowp = P + pidx((size_t)(row0 + ai * 128 + m * 16), col0);
; #pragma unroll
;                     for (int bj = 0; bj < 2; ++bj) { f32x4 v0 = acc[ai][bj][m][0], v1 = acc[ai][bj][m][1];
;                         if (sg) {
; #pragma unroll
;                             for (int i = 0; i < 4; ++i) { v0[i] = sigmoidf_(v0[i]); v1[i] = sigmoidf_(v1[i]); } }
;                         v4u w; w.x = pk2(v0[0], v0[1]); w.y = pk2(v0[2], v0[3]); w.z = pk2(v1[0], v1[1]); w.w = pk2(v1[2], v1[3]);
;                         __builtin_nontemporal_store(w, (v4u*)(rowp + bj * 128)); } }
.LBB0_159:
	s_ashr_i32 s65, s64, 31
	s_lshl_b64 s[2:3], s[64:65], 24
	s_add_u32 s2, s86, s2
	s_addc_u32 s3, s87, s3
	v_and_b32_e32 v202, 0xfffffff7, v180
	v_ashrrev_i32_e32 v203, 31, v202
	v_lshlrev_b64 v[202:203], 9, v[202:203]
	v_lshl_add_u64 v[202:203], s[2:3], 0, v[202:203]
	v_lshrrev_b32_e32 v204, 5, v154
	v_lshlrev_b32_e32 v204, 7, v204
	v_bfe_u32 v205, v154, 3, 2
	v_lshl_or_b32 v204, v205, 4, v204
	v_bfe_u32 v205, v180, 3, 1
	v_lshl_or_b32 v204, v205, 6, v204
	v_add_u32_e32 v204, 0x1000, v204
	v_mov_b32_e32 v205, 0
	v_lshl_add_u64 v[202:203], v[202:203], 0, v[204:205]
	s_cmp_lt_i32 s64, 26
	s_cbranch_scc1 .Lg1e_nosig
	v_mul_f32_e32 v126, 0xbfb8aa3b, v126
	v_mul_f32_e32 v127, 0xbfb8aa3b, v127
	v_mul_f32_e32 v128, 0xbfb8aa3b, v128
	v_mul_f32_e32 v129, 0xbfb8aa3b, v129
	v_mul_f32_e32 v122, 0xbfb8aa3b, v122
	v_mul_f32_e32 v123, 0xbfb8aa3b, v123
	v_mul_f32_e32 v124, 0xbfb8aa3b, v124
	v_mul_f32_e32 v125, 0xbfb8aa3b, v125
	v_exp_f32_e32 v126, v126
	v_exp_f32_e32 v127, v127
	v_exp_f32_e32 v128, v128
	v_exp_f32_e32 v129, v129
	v_exp_f32_e32 v122, v122
	v_exp_f32_e32 v123, v123
	v_exp_f32_e32 v124, v124
	v_exp_f32_e32 v125, v125
	v_add_f32_e32 v126, 1.0, v126
	v_add_f32_e32 v127, 1.0, v127
	v_add_f32_e32 v128, 1.0, v128
	v_add_f32_e32 v129, 1.0, v129
	v_add_f32_e32 v122, 1.0, v122
	v_add_f32_e32 v123, 1.0, v123
	v_add_f32_e32 v124, 1.0, v124
	v_add_f32_e32 v125, 1.0, v125
	v_rcp_f32_e32 v126, v126
	v_rcp_f32_e32 v127, v127
	v_rcp_f32_e32 v128, v128
	v_rcp_f32_e32 v129, v129
	v_rcp_f32_e32 v122, v122
	v_rcp_f32_e32 v123, v123
	v_rcp_f32_e32 v124, v124
	v_rcp_f32_e32 v125, v125
	v_mul_f32_e32 v118, 0xbfb8aa3b, v118
	v_mul_f32_e32 v119, 0xbfb8aa3b, v119
	v_mul_f32_e32 v120, 0xbfb8aa3b, v120
	v_mul_f32_e32 v121, 0xbfb8aa3b, v121
	v_mul_f32_e32 v114, 0xbfb8aa3b, v114
	v_mul_f32_e32 v115, 0xbfb8aa3b, v115
	v_mul_f32_e32 v116, 0xbfb8aa3b, v116
	v_mul_f32_e32 v117, 0xbfb8aa3b, v117
	v_exp_f32_e32 v118, v118
	v_exp_f32_e32 v119, v119
	v_exp_f32_e32 v120, v120
	v_exp_f32_e32 v121, v121
	v_exp_f32_e32 v114, v114
	v_exp_f32_e32 v115, v115
	v_exp_f32_e32 v116, v116
	v_exp_f32_e32 v117, v117
	v_add_f32_e32 v118, 1.0, v118
	v_add_f32_e32 v119, 1.0, v119
	v_add_f32_e32 v120, 1.0, v120
	v_add_f32_e32 v121, 1.0, v121
	v_add_f32_e32 v114, 1.0, v114
	v_add_f32_e32 v115, 1.0, v115
	v_add_f32_e32 v116, 1.0, v116
	v_add_f32_e32 v117, 1.0, v117
	v_rcp_f32_e32 v118, v118
	v_rcp_f32_e32 v119, v119
	v_rcp_f32_e32 v120, v120
	v_rcp_f32_e32 v121, v121
	v_rcp_f32_e32 v114, v114
	v_rcp_f32_e32 v115, v115
	v_rcp_f32_e32 v116, v116
	v_rcp_f32_e32 v117, v117
	v_cvt_pk_bf16_f32 v208, v126, v127
	v_cvt_pk_bf16_f32 v209, v128, v129
	v_cvt_pk_bf16_f32 v210, v122, v123
	v_cvt_pk_bf16_f32 v211, v124, v125
	v_cvt_pk_bf16_f32 v212, v118, v119
	v_cvt_pk_bf16_f32 v213, v120, v121
	v_cvt_pk_bf16_f32 v214, v114, v115
	v_cvt_pk_bf16_f32 v215, v116, v117
	v_mov_b32_e32 v216, v212
	v_mov_b32_e32 v217, v213
	v_mov_b32_e32 v218, v214
	v_mov_b32_e32 v219, v215
	v_mov_b32_dpp v212, v208 row_shl:8 row_mask:0xf bank_mask:0x3
	v_mov_b32_dpp v213, v209 row_shl:8 row_mask:0xf bank_mask:0x3
	v_mov_b32_dpp v214, v210 row_shl:8 row_mask:0xf bank_mask:0x3
	v_mov_b32_dpp v215, v211 row_shl:8 row_mask:0xf bank_mask:0x3
	v_mov_b32_dpp v208, v216 row_shr:8 row_mask:0xf bank_mask:0xc
	v_mov_b32_dpp v209, v217 row_shr:8 row_mask:0xf bank_mask:0xc
	v_mov_b32_dpp v210, v218 row_shr:8 row_mask:0xf bank_mask:0xc
	v_mov_b32_dpp v211, v219 row_shr:8 row_mask:0xf bank_mask:0xc
	global_store_dwordx4 v[202:203], v[208:211], off offset:-4096 nt
	global_store_dwordx4 v[202:203], v[212:215], off nt
	v_mul_f32_e32 v110, 0xbfb8aa3b, v110
	v_mul_f32_e32 v111, 0xbfb8aa3b, v111
	v_mul_f32_e32 v112, 0xbfb8aa3b, v112
	v_mul_f32_e32 v113, 0xbfb8aa3b, v113
	v_mul_f32_e32 v106, 0xbfb8aa3b, v106
	v_mul_f32_e32 v107, 0xbfb8aa3b, v107
	v_mul_f32_e32 v108, 0xbfb8aa3b, v108
	v_mul_f32_e32 v109, 0xbfb8aa3b, v109
	v_exp_f32_e32 v110, v110
	v_exp_f32_e32 v111, v111
	v_exp_f32_e32 v112, v112
	v_exp_f32_e32 v113, v113
	v_exp_f32_e32 v106, v106
	v_exp_f32_e32 v107, v107
	v_exp_f32_e32 v108, v108
	v_exp_f32_e32 v109, v109
	v_add_f32_e32 v110, 1.0, v110
	v_add_f32_e32 v111, 1.0, v111
	v_add_f32_e32 v112, 1.0, v112
	v_add_f32_e32 v113, 1.0, v113
	v_add_f32_e32 v106, 1.0, v106
	v_add_f32_e32 v107, 1.0, v107
	v_add_f32_e32 v108, 1.0, v108
	v_add_f32_e32 v109, 1.0, v109
	v_rcp_f32_e32 v110, v110
	v_rcp_f32_e32 v111, v111
	v_rcp_f32_e32 v112, v112
	v_rcp_f32_e32 v113, v113
	v_rcp_f32_e32 v106, v106
	v_rcp_f32_e32 v107, v107
	v_rcp_f32_e32 v108, v108
	v_rcp_f32_e32 v109, v109
	v_mul_f32_e32 v102, 0xbfb8aa3b, v102
	v_mul_f32_e32 v103, 0xbfb8aa3b, v103
	v_mul_f32_e32 v104, 0xbfb8aa3b, v104
	v_mul_f32_e32 v105, 0xbfb8aa3b, v105
	v_mul_f32_e32 v98, 0xbfb8aa3b, v98
	v_mul_f32_e32 v99, 0xbfb8aa3b, v99
	v_mul_f32_e32 v100, 0xbfb8aa3b, v100
	v_mul_f32_e32 v101, 0xbfb8aa3b, v101
	v_exp_f32_e32 v102, v102
	v_exp_f32_e32 v103, v103
	v_exp_f32_e32 v104, v104
	v_exp_f32_e32 v105, v105
	v_exp_f32_e32 v98, v98
	v_exp_f32_e32 v99, v99
	v_exp_f32_e32 v100, v100
	v_exp_f32_e32 v101, v101
	v_add_f32_e32 v102, 1.0, v102
	v_add_f32_e32 v103, 1.0, v103
	v_add_f32_e32 v104, 1.0, v104
	v_add_f32_e32 v105, 1.0, v105
	v_add_f32_e32 v98, 1.0, v98
	v_add_f32_e32 v99, 1.0, v99
	v_add_f32_e32 v100, 1.0, v100
	v_add_f32_e32 v101, 1.0, v101
	v_rcp_f32_e32 v102, v102
	v_rcp_f32_e32 v103, v103
	v_rcp_f32_e32 v104, v104
	v_rcp_f32_e32 v105, v105
	v_rcp_f32_e32 v98, v98
	v_rcp_f32_e32 v99, v99
	v_rcp_f32_e32 v100, v100
	v_rcp_f32_e32 v101, v101
	v_cvt_pk_bf16_f32 v224, v110, v111
	v_cvt_pk_bf16_f32 v225, v112, v113
	v_cvt_pk_bf16_f32 v226, v106, v107
	v_cvt_pk_bf16_f32 v227, v108, v109
; DI size_t pidx(size_t row, int col) { return (size_t)(col >> 8) * ((size_t)TH * 256) + row * 256 + (size_t)(col & 255); }
; DI unsigned pk2(float lo, float hi) { return pg8::cvt_pk_bf16(lo, hi); }
; DI float sigmoidf_(float v) { return __builtin_amdgcn_rcpf(1.0f + __expf(-v)); }
;     DI void operator()(const f32x4 (&acc)[2][2][4][2], const Unit& u, int wr, int wc, int fr, int fq) const {
;     ...
;             const int col0 = u.pn * 256 + wc * 32 + 8 * fq; const bool sg = u.pn >= 26;
; #pragma unroll
;             for (int ai = 0; ai < 2; ++ai)
; #pragma unroll
;                 for (int m = 0; m < 4; ++m) { bf16* rowp = P + pidx((size_t)(row0 + ai * 128 + m * 16), col0);
; #pragma unroll
;                     for (int bj = 0; bj < 2; ++bj) { f32x4 v0 = acc[ai][bj][m][0], v1 = acc[ai][bj][m][1];
;                         if (sg) {
; #pragma unroll
;                             for (int i = 0; i < 4; ++i) { v0[i] = sigmoidf_(v0[i]); v1[i] = sigmoidf_(v1[i]); } }
;                         v4u w; w.x = pk2(v0[0], v0[1]); w.y = pk2(v0[2], v0[3]); w.z = pk2(v1[0], v1[1]); w.w = pk2(v1[2], v1[3]);
;                         __builtin_nontemporal_store(w, (v4u*)(rowp + bj * 128)); } }
	v_cvt_pk_bf16_f32 v228, v102, v103
	v_cvt_pk_bf16_f32 v229, v104, v105
	v_cvt_pk_bf16_f32 v230, v98, v99
	v_cvt_pk_bf16_f32 v231, v100, v101
	v_mov_b32_e32 v232, v228
	v_mov_b32_e32 v233, v229
	v_mov_b32_e32 v234, v230
	v_mov_b32_e32 v235, v231
	v_mov_b32_dpp v228, v224 row_shl:8 row_mask:0xf bank_mask:0x3
	v_mov_b32_dpp v229, v225 row_shl:8 row_mask:0xf bank_mask:0x3
	v_mov_b32_dpp v230, v226 row_shl:8 row_mask:0xf bank_mask:0x3
	v_mov_b32_dpp v231, v227 row_shl:8 row_mask:0xf bank_mask:0x3
	v_mov_b32_dpp v224, v232 row_shr:8 row_mask:0xf bank_mask:0xc
	v_mov_b32_dpp v225, v233 row_shr:8 row_mask:0xf bank_mask:0xc
	v_mov_b32_dpp v226, v234 row_shr:8 row_mask:0xf bank_mask:0xc
	v_mov_b32_dpp v227, v235 row_shr:8 row_mask:0xf bank_mask:0xc
	s_mov_b64 s[98:99], 0x2000
	v_lshl_add_u64 v[206:207], v[202:203], 0, s[98:99]
	global_store_dwordx4 v[206:207], v[224:227], off offset:-4096 nt
	global_store_dwordx4 v[206:207], v[228:231], off nt
	v_mul_f32_e32 v94, 0xbfb8aa3b, v94
	v_mul_f32_e32 v95, 0xbfb8aa3b, v95
	v_mul_f32_e32 v96, 0xbfb8aa3b, v96
	v_mul_f32_e32 v97, 0xbfb8aa3b, v97
	v_mul_f32_e32 v90, 0xbfb8aa3b, v90
	v_mul_f32_e32 v91, 0xbfb8aa3b, v91
	v_mul_f32_e32 v92, 0xbfb8aa3b, v92
	v_mul_f32_e32 v93, 0xbfb8aa3b, v93
	v_exp_f32_e32 v94, v94
	v_exp_f32_e32 v95, v95
	v_exp_f32_e32 v96, v96
	v_exp_f32_e32 v97, v97
	v_exp_f32_e32 v90, v90
	v_exp_f32_e32 v91, v91
	v_exp_f32_e32 v92, v92
	v_exp_f32_e32 v93, v93
	v_add_f32_e32 v94, 1.0, v94
	v_add_f32_e32 v95, 1.0, v95
	v_add_f32_e32 v96, 1.0, v96
	v_add_f32_e32 v97, 1.0, v97
	v_add_f32_e32 v90, 1.0, v90
	v_add_f32_e32 v91, 1.0, v91
	v_add_f32_e32 v92, 1.0, v92
	v_add_f32_e32 v93, 1.0, v93
	v_rcp_f32_e32 v94, v94
	v_rcp_f32_e32 v95, v95
	v_rcp_f32_e32 v96, v96
	v_rcp_f32_e32 v97, v97
	v_rcp_f32_e32 v90, v90
	v_rcp_f32_e32 v91, v91
	v_rcp_f32_e32 v92, v92
	v_rcp_f32_e32 v93, v93
	v_mul_f32_e32 v86, 0xbfb8aa3b, v86
	v_mul_f32_e32 v87, 0xbfb8aa3b, v87
	v_mul_f32_e32 v88, 0xbfb8aa3b, v88
	v_mul_f32_e32 v89, 0xbfb8aa3b, v89
	v_mul_f32_e32 v82, 0xbfb8aa3b, v82
	v_mul_f32_e32 v83, 0xbfb8aa3b, v83
	v_mul_f32_e32 v84, 0xbfb8aa3b, v84
	v_mul_f32_e32 v85, 0xbfb8aa3b, v85
	v_exp_f32_e32 v86, v86
	v_exp_f32_e32 v87, v87
	v_exp_f32_e32 v88, v88
	v_exp_f32_e32 v89, v89
	v_exp_f32_e32 v82, v82
	v_exp_f32_e32 v83, v83
	v_exp_f32_e32 v84, v84
	v_exp_f32_e32 v85, v85
	v_add_f32_e32 v86, 1.0, v86
	v_add_f32_e32 v87, 1.0, v87
	v_add_f32_e32 v88, 1.0, v88
	v_add_f32_e32 v89, 1.0, v89
	v_add_f32_e32 v82, 1.0, v82
	v_add_f32_e32 v83, 1.0, v83
	v_add_f32_e32 v84, 1.0, v84
	v_add_f32_e32 v85, 1.0, v85
	v_rcp_f32_e32 v86, v86
	v_rcp_f32_e32 v87, v87
	v_rcp_f32_e32 v88, v88
	v_rcp_f32_e32 v89, v89
	v_rcp_f32_e32 v82, v82
	v_rcp_f32_e32 v83, v83
	v_rcp_f32_e32 v84, v84
	v_rcp_f32_e32 v85, v85
	v_cvt_pk_bf16_f32 v208, v94, v95
	v_cvt_pk_bf16_f32 v209, v96, v97
	v_cvt_pk_bf16_f32 v210, v90, v91
	v_cvt_pk_bf16_f32 v211, v92, v93
	v_cvt_pk_bf16_f32 v212, v86, v87
	v_cvt_pk_bf16_f32 v213, v88, v89
	v_cvt_pk_bf16_f32 v214, v82, v83
	v_cvt_pk_bf16_f32 v215, v84, v85
	v_mov_b32_e32 v216, v212
	v_mov_b32_e32 v217, v213
	v_mov_b32_e32 v218, v214
	v_mov_b32_e32 v219, v215
	v_mov_b32_dpp v212, v208 row_shl:8 row_mask:0xf bank_mask:0x3
	v_mov_b32_dpp v213, v209 row_shl:8 row_mask:0xf bank_mask:0x3
	v_mov_b32_dpp v214, v210 row_shl:8 row_mask:0xf bank_mask:0x3
	v_mov_b32_dpp v215, v211 row_shl:8 row_mask:0xf bank_mask:0x3
	v_mov_b32_dpp v208, v216 row_shr:8 row_mask:0xf bank_mask:0xc
	v_mov_b32_dpp v209, v217 row_shr:8 row_mask:0xf bank_mask:0xc
	v_mov_b32_dpp v210, v218 row_shr:8 row_mask:0xf bank_mask:0xc
	v_mov_b32_dpp v211, v219 row_shr:8 row_mask:0xf bank_mask:0xc
	s_mov_b64 s[98:99], 0x4000
	v_lshl_add_u64 v[206:207], v[202:203], 0, s[98:99]
	global_store_dwordx4 v[206:207], v[208:211], off offset:-4096 nt
	global_store_dwordx4 v[206:207], v[212:215], off nt
	v_mul_f32_e32 v78, 0xbfb8aa3b, v78
	v_mul_f32_e32 v79, 0xbfb8aa3b, v79
	v_mul_f32_e32 v80, 0xbfb8aa3b, v80
	v_mul_f32_e32 v81, 0xbfb8aa3b, v81
	v_mul_f32_e32 v74, 0xbfb8aa3b, v74
	v_mul_f32_e32 v75, 0xbfb8aa3b, v75
	v_mul_f32_e32 v76, 0xbfb8aa3b, v76
	v_mul_f32_e32 v77, 0xbfb8aa3b, v77
	v_exp_f32_e32 v78, v78
	v_exp_f32_e32 v79, v79
	v_exp_f32_e32 v80, v80
	v_exp_f32_e32 v81, v81
	v_exp_f32_e32 v74, v74
	v_exp_f32_e32 v75, v75
	v_exp_f32_e32 v76, v76
	v_exp_f32_e32 v77, v77
	v_add_f32_e32 v78, 1.0, v78
	v_add_f32_e32 v79, 1.0, v79
	v_add_f32_e32 v80, 1.0, v80
	v_add_f32_e32 v81, 1.0, v81
	v_add_f32_e32 v74, 1.0, v74
	v_add_f32_e32 v75, 1.0, v75
	v_add_f32_e32 v76, 1.0, v76
	v_add_f32_e32 v77, 1.0, v77
	v_rcp_f32_e32 v78, v78
	v_rcp_f32_e32 v79, v79
	v_rcp_f32_e32 v80, v80
	v_rcp_f32_e32 v81, v81
	v_rcp_f32_e32 v74, v74
	v_rcp_f32_e32 v75, v75
	v_rcp_f32_e32 v76, v76
	v_rcp_f32_e32 v77, v77
	v_mul_f32_e32 v70, 0xbfb8aa3b, v70
	v_mul_f32_e32 v71, 0xbfb8aa3b, v71
	v_mul_f32_e32 v72, 0xbfb8aa3b, v72
	v_mul_f32_e32 v73, 0xbfb8aa3b, v73
	v_mul_f32_e32 v66, 0xbfb8aa3b, v66
	v_mul_f32_e32 v67, 0xbfb8aa3b, v67
	v_mul_f32_e32 v68, 0xbfb8aa3b, v68
	v_mul_f32_e32 v69, 0xbfb8aa3b, v69
	v_exp_f32_e32 v70, v70
	v_exp_f32_e32 v71, v71
	v_exp_f32_e32 v72, v72
	v_exp_f32_e32 v73, v73
	v_exp_f32_e32 v66, v66
	v_exp_f32_e32 v67, v67
	v_exp_f32_e32 v68, v68
	v_exp_f32_e32 v69, v69
	v_add_f32_e32 v70, 1.0, v70
	v_add_f32_e32 v71, 1.0, v71
	v_add_f32_e32 v72, 1.0, v72
	v_add_f32_e32 v73, 1.0, v73
	v_add_f32_e32 v66, 1.0, v66
	v_add_f32_e32 v67, 1.0, v67
	v_add_f32_e32 v68, 1.0, v68
	v_add_f32_e32 v69, 1.0, v69
	v_rcp_f32_e32 v70, v70
	v_rcp_f32_e32 v71, v71
	v_rcp_f32_e32 v72, v72
	v_rcp_f32_e32 v73, v73
	v_rcp_f32_e32 v66, v66
	v_rcp_f32_e32 v67, v67
	v_rcp_f32_e32 v68, v68
	v_rcp_f32_e32 v69, v69
; DI size_t pidx(size_t row, int col) { return (size_t)(col >> 8) * ((size_t)TH * 256) + row * 256 + (size_t)(col & 255); }
; DI unsigned pk2(float lo, float hi) { return pg8::cvt_pk_bf16(lo, hi); }
; DI float sigmoidf_(float v) { return __builtin_amdgcn_rcpf(1.0f + __expf(-v)); }
;     DI void operator()(const f32x4 (&acc)[2][2][4][2], const Unit& u, int wr, int wc, int fr, int fq) const {
;     ...
;             const int col0 = u.pn * 256 + wc * 32 + 8 * fq; const bool sg = u.pn >= 26;
; #pragma unroll
;             for (int ai = 0; ai < 2; ++ai)
; #pragma unroll
;                 for (int m = 0; m < 4; ++m) { bf16* rowp = P + pidx((size_t)(row0 + ai * 128 + m * 16), col0);
; #pragma unroll
;                     for (int bj = 0; bj < 2; ++bj) { f32x4 v0 = acc[ai][bj][m][0], v1 = acc[ai][bj][m][1];
;                         if (sg) {
; #pragma unroll
;                             for (int i = 0; i < 4; ++i) { v0[i] = sigmoidf_(v0[i]); v1[i] = sigmoidf_(v1[i]); } }
;                         v4u w; w.x = pk2(v0[0], v0[1]); w.y = pk2(v0[2], v0[3]); w.z = pk2(v1[0], v1[1]); w.w = pk2(v1[2], v1[3]);
;                         __builtin_nontemporal_store(w, (v4u*)(rowp + bj * 128)); } }
	v_cvt_pk_bf16_f32 v224, v78, v79
	v_cvt_pk_bf16_f32 v225, v80, v81
	v_cvt_pk_bf16_f32 v226, v74, v75
	v_cvt_pk_bf16_f32 v227, v76, v77
	v_cvt_pk_bf16_f32 v228, v70, v71
	v_cvt_pk_bf16_f32 v229, v72, v73
	v_cvt_pk_bf16_f32 v230, v66, v67
	v_cvt_pk_bf16_f32 v231, v68, v69
	v_mov_b32_e32 v232, v228
	v_mov_b32_e32 v233, v229
	v_mov_b32_e32 v234, v230
	v_mov_b32_e32 v235, v231
	v_mov_b32_dpp v228, v224 row_shl:8 row_mask:0xf bank_mask:0x3
	v_mov_b32_dpp v229, v225 row_shl:8 row_mask:0xf bank_mask:0x3
	v_mov_b32_dpp v230, v226 row_shl:8 row_mask:0xf bank_mask:0x3
	v_mov_b32_dpp v231, v227 row_shl:8 row_mask:0xf bank_mask:0x3
	v_mov_b32_dpp v224, v232 row_shr:8 row_mask:0xf bank_mask:0xc
	v_mov_b32_dpp v225, v233 row_shr:8 row_mask:0xf bank_mask:0xc
	v_mov_b32_dpp v226, v234 row_shr:8 row_mask:0xf bank_mask:0xc
	v_mov_b32_dpp v227, v235 row_shr:8 row_mask:0xf bank_mask:0xc
	s_mov_b64 s[98:99], 0x6000
	v_lshl_add_u64 v[206:207], v[202:203], 0, s[98:99]
	global_store_dwordx4 v[206:207], v[224:227], off offset:-4096 nt
	global_store_dwordx4 v[206:207], v[228:231], off nt
	v_mul_f32_e32 v62, 0xbfb8aa3b, v62
	v_mul_f32_e32 v63, 0xbfb8aa3b, v63
	v_mul_f32_e32 v64, 0xbfb8aa3b, v64
	v_mul_f32_e32 v65, 0xbfb8aa3b, v65
	v_mul_f32_e32 v58, 0xbfb8aa3b, v58
	v_mul_f32_e32 v59, 0xbfb8aa3b, v59
	v_mul_f32_e32 v60, 0xbfb8aa3b, v60
	v_mul_f32_e32 v61, 0xbfb8aa3b, v61
	v_exp_f32_e32 v62, v62
	v_exp_f32_e32 v63, v63
	v_exp_f32_e32 v64, v64
	v_exp_f32_e32 v65, v65
	v_exp_f32_e32 v58, v58
	v_exp_f32_e32 v59, v59
	v_exp_f32_e32 v60, v60
	v_exp_f32_e32 v61, v61
	v_add_f32_e32 v62, 1.0, v62
	v_add_f32_e32 v63, 1.0, v63
	v_add_f32_e32 v64, 1.0, v64
	v_add_f32_e32 v65, 1.0, v65
	v_add_f32_e32 v58, 1.0, v58
	v_add_f32_e32 v59, 1.0, v59
	v_add_f32_e32 v60, 1.0, v60
	v_add_f32_e32 v61, 1.0, v61
	v_rcp_f32_e32 v62, v62
	v_rcp_f32_e32 v63, v63
	v_rcp_f32_e32 v64, v64
	v_rcp_f32_e32 v65, v65
	v_rcp_f32_e32 v58, v58
	v_rcp_f32_e32 v59, v59
	v_rcp_f32_e32 v60, v60
	v_rcp_f32_e32 v61, v61
	v_mul_f32_e32 v54, 0xbfb8aa3b, v54
	v_mul_f32_e32 v55, 0xbfb8aa3b, v55
	v_mul_f32_e32 v56, 0xbfb8aa3b, v56
	v_mul_f32_e32 v57, 0xbfb8aa3b, v57
	v_mul_f32_e32 v50, 0xbfb8aa3b, v50
	v_mul_f32_e32 v51, 0xbfb8aa3b, v51
	v_mul_f32_e32 v52, 0xbfb8aa3b, v52
	v_mul_f32_e32 v53, 0xbfb8aa3b, v53
	v_exp_f32_e32 v54, v54
	v_exp_f32_e32 v55, v55
	v_exp_f32_e32 v56, v56
	v_exp_f32_e32 v57, v57
	v_exp_f32_e32 v50, v50
	v_exp_f32_e32 v51, v51
	v_exp_f32_e32 v52, v52
	v_exp_f32_e32 v53, v53
	v_add_f32_e32 v54, 1.0, v54
	v_add_f32_e32 v55, 1.0, v55
	v_add_f32_e32 v56, 1.0, v56
	v_add_f32_e32 v57, 1.0, v57
	v_add_f32_e32 v50, 1.0, v50
	v_add_f32_e32 v51, 1.0, v51
	v_add_f32_e32 v52, 1.0, v52
	v_add_f32_e32 v53, 1.0, v53
	v_rcp_f32_e32 v54, v54
	v_rcp_f32_e32 v55, v55
	v_rcp_f32_e32 v56, v56
	v_rcp_f32_e32 v57, v57
	v_rcp_f32_e32 v50, v50
	v_rcp_f32_e32 v51, v51
	v_rcp_f32_e32 v52, v52
	v_rcp_f32_e32 v53, v53
	v_cvt_pk_bf16_f32 v208, v62, v63
	v_cvt_pk_bf16_f32 v209, v64, v65
	v_cvt_pk_bf16_f32 v210, v58, v59
	v_cvt_pk_bf16_f32 v211, v60, v61
	v_cvt_pk_bf16_f32 v212, v54, v55
	v_cvt_pk_bf16_f32 v213, v56, v57
	v_cvt_pk_bf16_f32 v214, v50, v51
	v_cvt_pk_bf16_f32 v215, v52, v53
	v_mov_b32_e32 v216, v212
	v_mov_b32_e32 v217, v213
	v_mov_b32_e32 v218, v214
	v_mov_b32_e32 v219, v215
	v_mov_b32_dpp v212, v208 row_shl:8 row_mask:0xf bank_mask:0x3
	v_mov_b32_dpp v213, v209 row_shl:8 row_mask:0xf bank_mask:0x3
	v_mov_b32_dpp v214, v210 row_shl:8 row_mask:0xf bank_mask:0x3
	v_mov_b32_dpp v215, v211 row_shl:8 row_mask:0xf bank_mask:0x3
	v_mov_b32_dpp v208, v216 row_shr:8 row_mask:0xf bank_mask:0xc
	v_mov_b32_dpp v209, v217 row_shr:8 row_mask:0xf bank_mask:0xc
	v_mov_b32_dpp v210, v218 row_shr:8 row_mask:0xf bank_mask:0xc
	v_mov_b32_dpp v211, v219 row_shr:8 row_mask:0xf bank_mask:0xc
	s_mov_b64 s[98:99], 0x10000
	v_lshl_add_u64 v[206:207], v[202:203], 0, s[98:99]
	global_store_dwordx4 v[206:207], v[208:211], off offset:-4096 nt
	global_store_dwordx4 v[206:207], v[212:215], off nt
	v_mul_f32_e32 v46, 0xbfb8aa3b, v46
	v_mul_f32_e32 v47, 0xbfb8aa3b, v47
	v_mul_f32_e32 v48, 0xbfb8aa3b, v48
	v_mul_f32_e32 v49, 0xbfb8aa3b, v49
	v_mul_f32_e32 v42, 0xbfb8aa3b, v42
	v_mul_f32_e32 v43, 0xbfb8aa3b, v43
	v_mul_f32_e32 v44, 0xbfb8aa3b, v44
	v_mul_f32_e32 v45, 0xbfb8aa3b, v45
	v_exp_f32_e32 v46, v46
	v_exp_f32_e32 v47, v47
	v_exp_f32_e32 v48, v48
	v_exp_f32_e32 v49, v49
	v_exp_f32_e32 v42, v42
	v_exp_f32_e32 v43, v43
	v_exp_f32_e32 v44, v44
	v_exp_f32_e32 v45, v45
	v_add_f32_e32 v46, 1.0, v46
	v_add_f32_e32 v47, 1.0, v47
	v_add_f32_e32 v48, 1.0, v48
	v_add_f32_e32 v49, 1.0, v49
	v_add_f32_e32 v42, 1.0, v42
	v_add_f32_e32 v43, 1.0, v43
	v_add_f32_e32 v44, 1.0, v44
	v_add_f32_e32 v45, 1.0, v45
	v_rcp_f32_e32 v46, v46
	v_rcp_f32_e32 v47, v47
	v_rcp_f32_e32 v48, v48
	v_rcp_f32_e32 v49, v49
	v_rcp_f32_e32 v42, v42
	v_rcp_f32_e32 v43, v43
	v_rcp_f32_e32 v44, v44
	v_rcp_f32_e32 v45, v45
	v_mul_f32_e32 v38, 0xbfb8aa3b, v38
	v_mul_f32_e32 v39, 0xbfb8aa3b, v39
	v_mul_f32_e32 v40, 0xbfb8aa3b, v40
	v_mul_f32_e32 v41, 0xbfb8aa3b, v41
	v_mul_f32_e32 v34, 0xbfb8aa3b, v34
	v_mul_f32_e32 v35, 0xbfb8aa3b, v35
	v_mul_f32_e32 v36, 0xbfb8aa3b, v36
	v_mul_f32_e32 v37, 0xbfb8aa3b, v37
	v_exp_f32_e32 v38, v38
	v_exp_f32_e32 v39, v39
	v_exp_f32_e32 v40, v40
	v_exp_f32_e32 v41, v41
	v_exp_f32_e32 v34, v34
	v_exp_f32_e32 v35, v35
	v_exp_f32_e32 v36, v36
	v_exp_f32_e32 v37, v37
	v_add_f32_e32 v38, 1.0, v38
	v_add_f32_e32 v39, 1.0, v39
	v_add_f32_e32 v40, 1.0, v40
	v_add_f32_e32 v41, 1.0, v41
	v_add_f32_e32 v34, 1.0, v34
	v_add_f32_e32 v35, 1.0, v35
	v_add_f32_e32 v36, 1.0, v36
	v_add_f32_e32 v37, 1.0, v37
	v_rcp_f32_e32 v38, v38
	v_rcp_f32_e32 v39, v39
; DI size_t pidx(size_t row, int col) { return (size_t)(col >> 8) * ((size_t)TH * 256) + row * 256 + (size_t)(col & 255); }
; DI unsigned pk2(float lo, float hi) { return pg8::cvt_pk_bf16(lo, hi); }
; DI float sigmoidf_(float v) { return __builtin_amdgcn_rcpf(1.0f + __expf(-v)); }
;     DI void operator()(const f32x4 (&acc)[2][2][4][2], const Unit& u, int wr, int wc, int fr, int fq) const {
;     ...
;             const int col0 = u.pn * 256 + wc * 32 + 8 * fq; const bool sg = u.pn >= 26;
; #pragma unroll
;             for (int ai = 0; ai < 2; ++ai)
; #pragma unroll
;                 for (int m = 0; m < 4; ++m) { bf16* rowp = P + pidx((size_t)(row0 + ai * 128 + m * 16), col0);
; #pragma unroll
;                     for (int bj = 0; bj < 2; ++bj) { f32x4 v0 = acc[ai][bj][m][0], v1 = acc[ai][bj][m][1];
;                         if (sg) {
; #pragma unroll
;                             for (int i = 0; i < 4; ++i) { v0[i] = sigmoidf_(v0[i]); v1[i] = sigmoidf_(v1[i]); } }
;                         v4u w; w.x = pk2(v0[0], v0[1]); w.y = pk2(v0[2], v0[3]); w.z = pk2(v1[0], v1[1]); w.w = pk2(v1[2], v1[3]);
;                         __builtin_nontemporal_store(w, (v4u*)(rowp + bj * 128)); } }
	v_rcp_f32_e32 v40, v40
	v_rcp_f32_e32 v41, v41
	v_rcp_f32_e32 v34, v34
	v_rcp_f32_e32 v35, v35
	v_rcp_f32_e32 v36, v36
	v_rcp_f32_e32 v37, v37
	v_cvt_pk_bf16_f32 v224, v46, v47
	v_cvt_pk_bf16_f32 v225, v48, v49
	v_cvt_pk_bf16_f32 v226, v42, v43
	v_cvt_pk_bf16_f32 v227, v44, v45
	v_cvt_pk_bf16_f32 v228, v38, v39
	v_cvt_pk_bf16_f32 v229, v40, v41
	v_cvt_pk_bf16_f32 v230, v34, v35
	v_cvt_pk_bf16_f32 v231, v36, v37
	v_mov_b32_e32 v232, v228
	v_mov_b32_e32 v233, v229
	v_mov_b32_e32 v234, v230
	v_mov_b32_e32 v235, v231
	v_mov_b32_dpp v228, v224 row_shl:8 row_mask:0xf bank_mask:0x3
	v_mov_b32_dpp v229, v225 row_shl:8 row_mask:0xf bank_mask:0x3
	v_mov_b32_dpp v230, v226 row_shl:8 row_mask:0xf bank_mask:0x3
	v_mov_b32_dpp v231, v227 row_shl:8 row_mask:0xf bank_mask:0x3
	v_mov_b32_dpp v224, v232 row_shr:8 row_mask:0xf bank_mask:0xc
	v_mov_b32_dpp v225, v233 row_shr:8 row_mask:0xf bank_mask:0xc
	v_mov_b32_dpp v226, v234 row_shr:8 row_mask:0xf bank_mask:0xc
	v_mov_b32_dpp v227, v235 row_shr:8 row_mask:0xf bank_mask:0xc
	s_mov_b64 s[98:99], 0x12000
	v_lshl_add_u64 v[206:207], v[202:203], 0, s[98:99]
	global_store_dwordx4 v[206:207], v[224:227], off offset:-4096 nt
	global_store_dwordx4 v[206:207], v[228:231], off nt
	v_mul_f32_e32 v30, 0xbfb8aa3b, v30
	v_mul_f32_e32 v31, 0xbfb8aa3b, v31
	v_mul_f32_e32 v32, 0xbfb8aa3b, v32
	v_mul_f32_e32 v33, 0xbfb8aa3b, v33
	v_mul_f32_e32 v26, 0xbfb8aa3b, v26
	v_mul_f32_e32 v27, 0xbfb8aa3b, v27
	v_mul_f32_e32 v28, 0xbfb8aa3b, v28
	v_mul_f32_e32 v29, 0xbfb8aa3b, v29
	v_exp_f32_e32 v30, v30
	v_exp_f32_e32 v31, v31
	v_exp_f32_e32 v32, v32
	v_exp_f32_e32 v33, v33
	v_exp_f32_e32 v26, v26
	v_exp_f32_e32 v27, v27
	v_exp_f32_e32 v28, v28
	v_exp_f32_e32 v29, v29
	v_add_f32_e32 v30, 1.0, v30
	v_add_f32_e32 v31, 1.0, v31
	v_add_f32_e32 v32, 1.0, v32
	v_add_f32_e32 v33, 1.0, v33
	v_add_f32_e32 v26, 1.0, v26
	v_add_f32_e32 v27, 1.0, v27
	v_add_f32_e32 v28, 1.0, v28
	v_add_f32_e32 v29, 1.0, v29
	v_rcp_f32_e32 v30, v30
	v_rcp_f32_e32 v31, v31
	v_rcp_f32_e32 v32, v32
	v_rcp_f32_e32 v33, v33
	v_rcp_f32_e32 v26, v26
	v_rcp_f32_e32 v27, v27
	v_rcp_f32_e32 v28, v28
	v_rcp_f32_e32 v29, v29
	v_mul_f32_e32 v22, 0xbfb8aa3b, v22
	v_mul_f32_e32 v23, 0xbfb8aa3b, v23
	v_mul_f32_e32 v24, 0xbfb8aa3b, v24
	v_mul_f32_e32 v25, 0xbfb8aa3b, v25
	v_mul_f32_e32 v18, 0xbfb8aa3b, v18
	v_mul_f32_e32 v19, 0xbfb8aa3b, v19
	v_mul_f32_e32 v20, 0xbfb8aa3b, v20
	v_mul_f32_e32 v21, 0xbfb8aa3b, v21
	v_exp_f32_e32 v22, v22
	v_exp_f32_e32 v23, v23
	v_exp_f32_e32 v24, v24
	v_exp_f32_e32 v25, v25
	v_exp_f32_e32 v18, v18
	v_exp_f32_e32 v19, v19
	v_exp_f32_e32 v20, v20
	v_exp_f32_e32 v21, v21
	v_add_f32_e32 v22, 1.0, v22
	v_add_f32_e32 v23, 1.0, v23
	v_add_f32_e32 v24, 1.0, v24
	v_add_f32_e32 v25, 1.0, v25
	v_add_f32_e32 v18, 1.0, v18
	v_add_f32_e32 v19, 1.0, v19
	v_add_f32_e32 v20, 1.0, v20
	v_add_f32_e32 v21, 1.0, v21
	v_rcp_f32_e32 v22, v22
	v_rcp_f32_e32 v23, v23
	v_rcp_f32_e32 v24, v24
	v_rcp_f32_e32 v25, v25
	v_rcp_f32_e32 v18, v18
	v_rcp_f32_e32 v19, v19
	v_rcp_f32_e32 v20, v20
	v_rcp_f32_e32 v21, v21
	v_cvt_pk_bf16_f32 v208, v30, v31
	v_cvt_pk_bf16_f32 v209, v32, v33
	v_cvt_pk_bf16_f32 v210, v26, v27
	v_cvt_pk_bf16_f32 v211, v28, v29
	v_cvt_pk_bf16_f32 v212, v22, v23
	v_cvt_pk_bf16_f32 v213, v24, v25
	v_cvt_pk_bf16_f32 v214, v18, v19
	v_cvt_pk_bf16_f32 v215, v20, v21
	v_mov_b32_e32 v216, v212
	v_mov_b32_e32 v217, v213
	v_mov_b32_e32 v218, v214
	v_mov_b32_e32 v219, v215
	v_mov_b32_dpp v212, v208 row_shl:8 row_mask:0xf bank_mask:0x3
	v_mov_b32_dpp v213, v209 row_shl:8 row_mask:0xf bank_mask:0x3
	v_mov_b32_dpp v214, v210 row_shl:8 row_mask:0xf bank_mask:0x3
	v_mov_b32_dpp v215, v211 row_shl:8 row_mask:0xf bank_mask:0x3
	v_mov_b32_dpp v208, v216 row_shr:8 row_mask:0xf bank_mask:0xc
	v_mov_b32_dpp v209, v217 row_shr:8 row_mask:0xf bank_mask:0xc
	v_mov_b32_dpp v210, v218 row_shr:8 row_mask:0xf bank_mask:0xc
	v_mov_b32_dpp v211, v219 row_shr:8 row_mask:0xf bank_mask:0xc
	s_mov_b64 s[98:99], 0x14000
	v_lshl_add_u64 v[206:207], v[202:203], 0, s[98:99]
	global_store_dwordx4 v[206:207], v[208:211], off offset:-4096 nt
	global_store_dwordx4 v[206:207], v[212:215], off nt
	v_mul_f32_e32 v14, 0xbfb8aa3b, v14
	v_mul_f32_e32 v15, 0xbfb8aa3b, v15
	v_mul_f32_e32 v16, 0xbfb8aa3b, v16
	v_mul_f32_e32 v17, 0xbfb8aa3b, v17
	v_mul_f32_e32 v10, 0xbfb8aa3b, v10
	v_mul_f32_e32 v11, 0xbfb8aa3b, v11
	v_mul_f32_e32 v12, 0xbfb8aa3b, v12
	v_mul_f32_e32 v13, 0xbfb8aa3b, v13
	v_exp_f32_e32 v14, v14
	v_exp_f32_e32 v15, v15
	v_exp_f32_e32 v16, v16
	v_exp_f32_e32 v17, v17
	v_exp_f32_e32 v10, v10
	v_exp_f32_e32 v11, v11
	v_exp_f32_e32 v12, v12
	v_exp_f32_e32 v13, v13
	v_add_f32_e32 v14, 1.0, v14
	v_add_f32_e32 v15, 1.0, v15
	v_add_f32_e32 v16, 1.0, v16
	v_add_f32_e32 v17, 1.0, v17
	v_add_f32_e32 v10, 1.0, v10
	v_add_f32_e32 v11, 1.0, v11
	v_add_f32_e32 v12, 1.0, v12
	v_add_f32_e32 v13, 1.0, v13
	v_rcp_f32_e32 v14, v14
	v_rcp_f32_e32 v15, v15
	v_rcp_f32_e32 v16, v16
	v_rcp_f32_e32 v17, v17
	v_rcp_f32_e32 v10, v10
	v_rcp_f32_e32 v11, v11
	v_rcp_f32_e32 v12, v12
	v_rcp_f32_e32 v13, v13
	v_mul_f32_e32 v6, 0xbfb8aa3b, v6
	v_mul_f32_e32 v7, 0xbfb8aa3b, v7
	v_mul_f32_e32 v8, 0xbfb8aa3b, v8
	v_mul_f32_e32 v9, 0xbfb8aa3b, v9
	v_mul_f32_e32 v2, 0xbfb8aa3b, v2
	v_mul_f32_e32 v3, 0xbfb8aa3b, v3
	v_mul_f32_e32 v4, 0xbfb8aa3b, v4
	v_mul_f32_e32 v5, 0xbfb8aa3b, v5
	v_exp_f32_e32 v6, v6
	v_exp_f32_e32 v7, v7
	v_exp_f32_e32 v8, v8
	v_exp_f32_e32 v9, v9
	v_exp_f32_e32 v2, v2
	v_exp_f32_e32 v3, v3
	v_exp_f32_e32 v4, v4
	v_exp_f32_e32 v5, v5
	v_add_f32_e32 v6, 1.0, v6
	v_add_f32_e32 v7, 1.0, v7
	v_add_f32_e32 v8, 1.0, v8
	v_add_f32_e32 v9, 1.0, v9
	v_add_f32_e32 v2, 1.0, v2
	v_add_f32_e32 v3, 1.0, v3
	v_add_f32_e32 v4, 1.0, v4
	v_add_f32_e32 v5, 1.0, v5
	v_rcp_f32_e32 v6, v6
	v_rcp_f32_e32 v7, v7
	v_rcp_f32_e32 v8, v8
	v_rcp_f32_e32 v9, v9
	v_rcp_f32_e32 v2, v2
	v_rcp_f32_e32 v3, v3
	v_rcp_f32_e32 v4, v4
	v_rcp_f32_e32 v5, v5
	v_cvt_pk_bf16_f32 v224, v14, v15
	v_cvt_pk_bf16_f32 v225, v16, v17
	v_cvt_pk_bf16_f32 v226, v10, v11
	v_cvt_pk_bf16_f32 v227, v12, v13
	v_cvt_pk_bf16_f32 v228, v6, v7
	v_cvt_pk_bf16_f32 v229, v8, v9
	v_cvt_pk_bf16_f32 v230, v2, v3
	v_cvt_pk_bf16_f32 v231, v4, v5
	v_mov_b32_e32 v232, v228
	v_mov_b32_e32 v233, v229
	v_mov_b32_e32 v234, v230
	v_mov_b32_e32 v235, v231
	v_mov_b32_dpp v228, v224 row_shl:8 row_mask:0xf bank_mask:0x3
	v_mov_b32_dpp v229, v225 row_shl:8 row_mask:0xf bank_mask:0x3
	v_mov_b32_dpp v230, v226 row_shl:8 row_mask:0xf bank_mask:0x3
	v_mov_b32_dpp v231, v227 row_shl:8 row_mask:0xf bank_mask:0x3
	v_mov_b32_dpp v224, v232 row_shr:8 row_mask:0xf bank_mask:0xc
	v_mov_b32_dpp v225, v233 row_shr:8 row_mask:0xf bank_mask:0xc
	v_mov_b32_dpp v226, v234 row_shr:8 row_mask:0xf bank_mask:0xc
	v_mov_b32_dpp v227, v235 row_shr:8 row_mask:0xf bank_mask:0xc
	s_mov_b64 s[98:99], 0x16000
	v_lshl_add_u64 v[206:207], v[202:203], 0, s[98:99]
	global_store_dwordx4 v[206:207], v[224:227], off offset:-4096 nt
	global_store_dwordx4 v[206:207], v[228:231], off nt
	s_branch .Lg1e_done
; DI size_t pidx(size_t row, int col) { return (size_t)(col >> 8) * ((size_t)TH * 256) + row * 256 + (size_t)(col & 255); }
; DI unsigned pk2(float lo, float hi) { return pg8::cvt_pk_bf16(lo, hi); }
; DI float sigmoidf_(float v) { return __builtin_amdgcn_rcpf(1.0f + __expf(-v)); }
;     DI void operator()(const f32x4 (&acc)[2][2][4][2], const Unit& u, int wr, int wc, int fr, int fq) const {
;     ...
;                 for (int m = 0; m < 4; ++m) { bf16* rowp = P + pidx((size_t)(row0 + ai * 128 + m * 16), col0);
; #pragma unroll
;                     for (int bj = 0; bj < 2; ++bj) { f32x4 v0 = acc[ai][bj][m][0], v1 = acc[ai][bj][m][1];
;                         if (sg) {
; #pragma unroll
;                             for (int i = 0; i < 4; ++i) { v0[i] = sigmoidf_(v0[i]); v1[i] = sigmoidf_(v1[i]); } }
;                         v4u w; w.x = pk2(v0[0], v0[1]); w.y = pk2(v0[2], v0[3]); w.z = pk2(v1[0], v1[1]); w.w = pk2(v1[2], v1[3]);
;                         __builtin_nontemporal_store(w, (v4u*)(rowp + bj * 128)); } }
.Lg1e_nosig:
	v_cvt_pk_bf16_f32 v208, v126, v127
	v_cvt_pk_bf16_f32 v209, v128, v129
	v_cvt_pk_bf16_f32 v210, v122, v123
	v_cvt_pk_bf16_f32 v211, v124, v125
	v_cvt_pk_bf16_f32 v212, v118, v119
	v_cvt_pk_bf16_f32 v213, v120, v121
	v_cvt_pk_bf16_f32 v214, v114, v115
	v_cvt_pk_bf16_f32 v215, v116, v117
	v_mov_b32_e32 v216, v212
	v_mov_b32_e32 v217, v213
	v_mov_b32_e32 v218, v214
	v_mov_b32_e32 v219, v215
	v_mov_b32_dpp v212, v208 row_shl:8 row_mask:0xf bank_mask:0x3
	v_mov_b32_dpp v213, v209 row_shl:8 row_mask:0xf bank_mask:0x3
	v_mov_b32_dpp v214, v210 row_shl:8 row_mask:0xf bank_mask:0x3
	v_mov_b32_dpp v215, v211 row_shl:8 row_mask:0xf bank_mask:0x3
	v_mov_b32_dpp v208, v216 row_shr:8 row_mask:0xf bank_mask:0xc
	v_mov_b32_dpp v209, v217 row_shr:8 row_mask:0xf bank_mask:0xc
	v_mov_b32_dpp v210, v218 row_shr:8 row_mask:0xf bank_mask:0xc
	v_mov_b32_dpp v211, v219 row_shr:8 row_mask:0xf bank_mask:0xc
	global_store_dwordx4 v[202:203], v[208:211], off offset:-4096 nt
	global_store_dwordx4 v[202:203], v[212:215], off nt
	v_cvt_pk_bf16_f32 v224, v110, v111
	v_cvt_pk_bf16_f32 v225, v112, v113
	v_cvt_pk_bf16_f32 v226, v106, v107
	v_cvt_pk_bf16_f32 v227, v108, v109
	v_cvt_pk_bf16_f32 v228, v102, v103
	v_cvt_pk_bf16_f32 v229, v104, v105
	v_cvt_pk_bf16_f32 v230, v98, v99
	v_cvt_pk_bf16_f32 v231, v100, v101
	v_mov_b32_e32 v232, v228
	v_mov_b32_e32 v233, v229
	v_mov_b32_e32 v234, v230
	v_mov_b32_e32 v235, v231
	v_mov_b32_dpp v228, v224 row_shl:8 row_mask:0xf bank_mask:0x3
	v_mov_b32_dpp v229, v225 row_shl:8 row_mask:0xf bank_mask:0x3
	v_mov_b32_dpp v230, v226 row_shl:8 row_mask:0xf bank_mask:0x3
	v_mov_b32_dpp v231, v227 row_shl:8 row_mask:0xf bank_mask:0x3
	v_mov_b32_dpp v224, v232 row_shr:8 row_mask:0xf bank_mask:0xc
	v_mov_b32_dpp v225, v233 row_shr:8 row_mask:0xf bank_mask:0xc
	v_mov_b32_dpp v226, v234 row_shr:8 row_mask:0xf bank_mask:0xc
	v_mov_b32_dpp v227, v235 row_shr:8 row_mask:0xf bank_mask:0xc
	s_mov_b64 s[98:99], 0x2000
	v_lshl_add_u64 v[206:207], v[202:203], 0, s[98:99]
	global_store_dwordx4 v[206:207], v[224:227], off offset:-4096 nt
	global_store_dwordx4 v[206:207], v[228:231], off nt
	v_cvt_pk_bf16_f32 v208, v94, v95
	v_cvt_pk_bf16_f32 v209, v96, v97
	v_cvt_pk_bf16_f32 v210, v90, v91
	v_cvt_pk_bf16_f32 v211, v92, v93
	v_cvt_pk_bf16_f32 v212, v86, v87
	v_cvt_pk_bf16_f32 v213, v88, v89
	v_cvt_pk_bf16_f32 v214, v82, v83
	v_cvt_pk_bf16_f32 v215, v84, v85
	v_mov_b32_e32 v216, v212
	v_mov_b32_e32 v217, v213
	v_mov_b32_e32 v218, v214
	v_mov_b32_e32 v219, v215
	v_mov_b32_dpp v212, v208 row_shl:8 row_mask:0xf bank_mask:0x3
	v_mov_b32_dpp v213, v209 row_shl:8 row_mask:0xf bank_mask:0x3
	v_mov_b32_dpp v214, v210 row_shl:8 row_mask:0xf bank_mask:0x3
	v_mov_b32_dpp v215, v211 row_shl:8 row_mask:0xf bank_mask:0x3
	v_mov_b32_dpp v208, v216 row_shr:8 row_mask:0xf bank_mask:0xc
	v_mov_b32_dpp v209, v217 row_shr:8 row_mask:0xf bank_mask:0xc
	v_mov_b32_dpp v210, v218 row_shr:8 row_mask:0xf bank_mask:0xc
	v_mov_b32_dpp v211, v219 row_shr:8 row_mask:0xf bank_mask:0xc
	s_mov_b64 s[98:99], 0x4000
	v_lshl_add_u64 v[206:207], v[202:203], 0, s[98:99]
	global_store_dwordx4 v[206:207], v[208:211], off offset:-4096 nt
	global_store_dwordx4 v[206:207], v[212:215], off nt
	v_cvt_pk_bf16_f32 v224, v78, v79
	v_cvt_pk_bf16_f32 v225, v80, v81
	v_cvt_pk_bf16_f32 v226, v74, v75
	v_cvt_pk_bf16_f32 v227, v76, v77
	v_cvt_pk_bf16_f32 v228, v70, v71
	v_cvt_pk_bf16_f32 v229, v72, v73
	v_cvt_pk_bf16_f32 v230, v66, v67
	v_cvt_pk_bf16_f32 v231, v68, v69
	v_mov_b32_e32 v232, v228
	v_mov_b32_e32 v233, v229
	v_mov_b32_e32 v234, v230
	v_mov_b32_e32 v235, v231
	v_mov_b32_dpp v228, v224 row_shl:8 row_mask:0xf bank_mask:0x3
	v_mov_b32_dpp v229, v225 row_shl:8 row_mask:0xf bank_mask:0x3
	v_mov_b32_dpp v230, v226 row_shl:8 row_mask:0xf bank_mask:0x3
	v_mov_b32_dpp v231, v227 row_shl:8 row_mask:0xf bank_mask:0x3
	v_mov_b32_dpp v224, v232 row_shr:8 row_mask:0xf bank_mask:0xc
	v_mov_b32_dpp v225, v233 row_shr:8 row_mask:0xf bank_mask:0xc
	v_mov_b32_dpp v226, v234 row_shr:8 row_mask:0xf bank_mask:0xc
	v_mov_b32_dpp v227, v235 row_shr:8 row_mask:0xf bank_mask:0xc
	s_mov_b64 s[98:99], 0x6000
	v_lshl_add_u64 v[206:207], v[202:203], 0, s[98:99]
	global_store_dwordx4 v[206:207], v[224:227], off offset:-4096 nt
	global_store_dwordx4 v[206:207], v[228:231], off nt
	v_cvt_pk_bf16_f32 v208, v62, v63
	v_cvt_pk_bf16_f32 v209, v64, v65
; DI size_t pidx(size_t row, int col) { return (size_t)(col >> 8) * ((size_t)TH * 256) + row * 256 + (size_t)(col & 255); }
; DI unsigned pk2(float lo, float hi) { return pg8::cvt_pk_bf16(lo, hi); }
; DI float sigmoidf_(float v) { return __builtin_amdgcn_rcpf(1.0f + __expf(-v)); }
; template <class Epi, class Sched, bool ALIGN_EPI = false, bool SP2 = false>
; __device__ __forceinline__ void gemm_phase(PG8_LAS unsigned char* lds, const Gemm g, const Sched& S, const Epi& E) {
;     ...
;         if (!has_next) break;
;     DI void operator()(const f32x4 (&acc)[2][2][4][2], const Unit& u, int wr, int wc, int fr, int fq) const {
;     ...
;                 for (int m = 0; m < 4; ++m) { bf16* rowp = P + pidx((size_t)(row0 + ai * 128 + m * 16), col0);
; #pragma unroll
;                     for (int bj = 0; bj < 2; ++bj) { f32x4 v0 = acc[ai][bj][m][0], v1 = acc[ai][bj][m][1];
;                         if (sg) {
; #pragma unroll
;                             for (int i = 0; i < 4; ++i) { v0[i] = sigmoidf_(v0[i]); v1[i] = sigmoidf_(v1[i]); } }
;                         v4u w; w.x = pk2(v0[0], v0[1]); w.y = pk2(v0[2], v0[3]); w.z = pk2(v1[0], v1[1]); w.w = pk2(v1[2], v1[3]);
;                         __builtin_nontemporal_store(w, (v4u*)(rowp + bj * 128)); } }
	v_cvt_pk_bf16_f32 v210, v58, v59
	v_cvt_pk_bf16_f32 v211, v60, v61
	v_cvt_pk_bf16_f32 v212, v54, v55
	v_cvt_pk_bf16_f32 v213, v56, v57
	v_cvt_pk_bf16_f32 v214, v50, v51
	v_cvt_pk_bf16_f32 v215, v52, v53
	v_mov_b32_e32 v216, v212
	v_mov_b32_e32 v217, v213
	v_mov_b32_e32 v218, v214
	v_mov_b32_e32 v219, v215
	v_mov_b32_dpp v212, v208 row_shl:8 row_mask:0xf bank_mask:0x3
	v_mov_b32_dpp v213, v209 row_shl:8 row_mask:0xf bank_mask:0x3
	v_mov_b32_dpp v214, v210 row_shl:8 row_mask:0xf bank_mask:0x3
	v_mov_b32_dpp v215, v211 row_shl:8 row_mask:0xf bank_mask:0x3
	v_mov_b32_dpp v208, v216 row_shr:8 row_mask:0xf bank_mask:0xc
	v_mov_b32_dpp v209, v217 row_shr:8 row_mask:0xf bank_mask:0xc
	v_mov_b32_dpp v210, v218 row_shr:8 row_mask:0xf bank_mask:0xc
	v_mov_b32_dpp v211, v219 row_shr:8 row_mask:0xf bank_mask:0xc
	s_mov_b64 s[98:99], 0x10000
	v_lshl_add_u64 v[206:207], v[202:203], 0, s[98:99]
	global_store_dwordx4 v[206:207], v[208:211], off offset:-4096 nt
	global_store_dwordx4 v[206:207], v[212:215], off nt
	v_cvt_pk_bf16_f32 v224, v46, v47
	v_cvt_pk_bf16_f32 v225, v48, v49
	v_cvt_pk_bf16_f32 v226, v42, v43
	v_cvt_pk_bf16_f32 v227, v44, v45
	v_cvt_pk_bf16_f32 v228, v38, v39
	v_cvt_pk_bf16_f32 v229, v40, v41
	v_cvt_pk_bf16_f32 v230, v34, v35
	v_cvt_pk_bf16_f32 v231, v36, v37
	v_mov_b32_e32 v232, v228
	v_mov_b32_e32 v233, v229
	v_mov_b32_e32 v234, v230
	v_mov_b32_e32 v235, v231
	v_mov_b32_dpp v228, v224 row_shl:8 row_mask:0xf bank_mask:0x3
	v_mov_b32_dpp v229, v225 row_shl:8 row_mask:0xf bank_mask:0x3
	v_mov_b32_dpp v230, v226 row_shl:8 row_mask:0xf bank_mask:0x3
	v_mov_b32_dpp v231, v227 row_shl:8 row_mask:0xf bank_mask:0x3
	v_mov_b32_dpp v224, v232 row_shr:8 row_mask:0xf bank_mask:0xc
	v_mov_b32_dpp v225, v233 row_shr:8 row_mask:0xf bank_mask:0xc
	v_mov_b32_dpp v226, v234 row_shr:8 row_mask:0xf bank_mask:0xc
	v_mov_b32_dpp v227, v235 row_shr:8 row_mask:0xf bank_mask:0xc
	s_mov_b64 s[98:99], 0x12000
	v_lshl_add_u64 v[206:207], v[202:203], 0, s[98:99]
	global_store_dwordx4 v[206:207], v[224:227], off offset:-4096 nt
	global_store_dwordx4 v[206:207], v[228:231], off nt
	v_cvt_pk_bf16_f32 v208, v30, v31
	v_cvt_pk_bf16_f32 v209, v32, v33
	v_cvt_pk_bf16_f32 v210, v26, v27
	v_cvt_pk_bf16_f32 v211, v28, v29
	v_cvt_pk_bf16_f32 v212, v22, v23
	v_cvt_pk_bf16_f32 v213, v24, v25
	v_cvt_pk_bf16_f32 v214, v18, v19
	v_cvt_pk_bf16_f32 v215, v20, v21
	v_mov_b32_e32 v216, v212
	v_mov_b32_e32 v217, v213
	v_mov_b32_e32 v218, v214
	v_mov_b32_e32 v219, v215
	v_mov_b32_dpp v212, v208 row_shl:8 row_mask:0xf bank_mask:0x3
	v_mov_b32_dpp v213, v209 row_shl:8 row_mask:0xf bank_mask:0x3
	v_mov_b32_dpp v214, v210 row_shl:8 row_mask:0xf bank_mask:0x3
	v_mov_b32_dpp v215, v211 row_shl:8 row_mask:0xf bank_mask:0x3
	v_mov_b32_dpp v208, v216 row_shr:8 row_mask:0xf bank_mask:0xc
	v_mov_b32_dpp v209, v217 row_shr:8 row_mask:0xf bank_mask:0xc
	v_mov_b32_dpp v210, v218 row_shr:8 row_mask:0xf bank_mask:0xc
	v_mov_b32_dpp v211, v219 row_shr:8 row_mask:0xf bank_mask:0xc
	s_mov_b64 s[98:99], 0x14000
	v_lshl_add_u64 v[206:207], v[202:203], 0, s[98:99]
	global_store_dwordx4 v[206:207], v[208:211], off offset:-4096 nt
	global_store_dwordx4 v[206:207], v[212:215], off nt
	v_cvt_pk_bf16_f32 v224, v14, v15
	v_cvt_pk_bf16_f32 v225, v16, v17
	v_cvt_pk_bf16_f32 v226, v10, v11
	v_cvt_pk_bf16_f32 v227, v12, v13
	v_cvt_pk_bf16_f32 v228, v6, v7
	v_cvt_pk_bf16_f32 v229, v8, v9
	v_cvt_pk_bf16_f32 v230, v2, v3
	v_cvt_pk_bf16_f32 v231, v4, v5
	v_mov_b32_e32 v232, v228
	v_mov_b32_e32 v233, v229
	v_mov_b32_e32 v234, v230
	v_mov_b32_e32 v235, v231
	v_mov_b32_dpp v228, v224 row_shl:8 row_mask:0xf bank_mask:0x3
	v_mov_b32_dpp v229, v225 row_shl:8 row_mask:0xf bank_mask:0x3
	v_mov_b32_dpp v230, v226 row_shl:8 row_mask:0xf bank_mask:0x3
	v_mov_b32_dpp v231, v227 row_shl:8 row_mask:0xf bank_mask:0x3
	v_mov_b32_dpp v224, v232 row_shr:8 row_mask:0xf bank_mask:0xc
	v_mov_b32_dpp v225, v233 row_shr:8 row_mask:0xf bank_mask:0xc
	v_mov_b32_dpp v226, v234 row_shr:8 row_mask:0xf bank_mask:0xc
	v_mov_b32_dpp v227, v235 row_shr:8 row_mask:0xf bank_mask:0xc
	s_mov_b64 s[98:99], 0x16000
	v_lshl_add_u64 v[206:207], v[202:203], 0, s[98:99]
	global_store_dwordx4 v[206:207], v[224:227], off offset:-4096 nt
	global_store_dwordx4 v[206:207], v[228:231], off nt
.Lg1e_done:
	s_andn2_b64 vcc, exec, s[4:5]
	s_mov_b64 s[2:3], -1
	s_cbranch_vccnz .LBB0_151
	s_branch .LBB0_213
